# adds: attention output via LDS transpose + 16B stores, GEMM tile prologue second DMA batch issued before first wait
# baseline (speedup 1.0000x reference)
.LBB0_291:
	v_and_b32_e32 v27, 15, v26
	v_and_b32_e32 v28, 48, v26
	v_lshlrev_b32_e32 v27, 6, v27
	v_lshlrev_b32_e32 v26, 2, v26
	s_lshl_b32 s25, s25, 12
	s_add_i32 m0, s30, 0x18000
	v_lshl_add_u64 v[8:9], v[8:9], 0, s[36:37]
	v_or_b32_e32 v29, v27, v28
	v_and_b32_e32 v26, 32, v26
	s_lshl_b32 s24, s24, 13
	s_and_b32 s25, s25, 0x3000
	global_load_lds_dwordx4 v[8:9], off
	v_lshl_add_u64 v[6:7], v[6:7], 0, s[36:37]
	s_add_i32 m0, s30, 0x1a000
	s_add_i32 s47, s30, 0x8000
	s_add_i32 s48, s30, 0xa000
	v_bitop3_b32 v27, v27, v26, v28 bitop3:0x36
	v_bitop3_b32 v26, v29, s24, v26 bitop3:0xde
	global_load_lds_dwordx4 v[6:7], off
	v_lshl_add_u64 v[4:5], v[4:5], 0, s[36:37]
	s_mov_b32 m0, s47
	s_add_u32 s24, s38, 0x20080
	v_or_b32_e32 v142, s25, v27
	global_load_lds_dwordx4 v[4:5], off
	v_lshl_add_u64 v[2:3], v[2:3], 0, s[36:37]
	s_mov_b32 m0, s48
	s_addc_u32 s25, s39, 0
	global_load_lds_dwordx4 v[2:3], off
	s_add_i32 m0, s30, 0x1c000
	v_lshl_add_u64 v[2:3], s[24:25], 0, v[112:113]
	global_load_lds_dwordx4 v[2:3], off
	v_lshl_add_u64 v[0:1], s[24:25], 0, v[0:1]
	s_add_i32 m0, s30, 0x1e000
	v_readlane_b32 s24, v252, 13
	global_load_lds_dwordx4 v[0:1], off
	s_waitcnt vmcnt(8)
	s_barrier
	v_lshlrev_b32_e32 v0, 12, v18
	v_and_b32_e32 v0, 0x7fffe000, v0
	v_lshl_add_u32 v0, v19, 9, v0
	v_or_b32_e32 v0, v0, v20
	v_add_lshl_u32 v112, v0, v21, 1
	v_lshlrev_b32_e32 v0, 12, v22
	v_and_b32_e32 v0, 0x7fffe000, v0
	v_readlane_b32 s25, v252, 14
	s_add_u32 s12, s24, s12
	v_lshl_add_u32 v0, v23, 9, v0
	s_addc_u32 s13, s25, s13
	v_or_b32_e32 v0, v0, v24
	v_lshl_add_u64 v[134:135], s[12:13], 0, v[112:113]
	v_add_lshl_u32 v112, v0, v25, 1
	v_lshlrev_b32_e32 v0, 17, v10
	v_and_b32_e32 v0, 0x7ffc0000, v0
	v_lshl_add_u32 v0, v11, 14, v0
	v_or_b32_e32 v0, v0, v12
	v_lshl_add_u64 v[136:137], s[12:13], 0, v[112:113]
	v_add_lshl_u32 v112, v0, v13, 1
	v_lshlrev_b32_e32 v0, 17, v14
	v_and_b32_e32 v0, 0x7ffc0000, v0
	s_add_u32 s6, s8, s6
	v_lshl_add_u32 v0, v15, 14, v0
	s_waitcnt vmcnt(6)
	s_addc_u32 s7, s9, s7
	v_or_b32_e32 v0, v0, v16
	v_lshl_add_u64 v[138:139], s[6:7], 0, v[112:113]
	v_add_lshl_u32 v112, v0, v17, 1
	v_mov_b32_e32 v0, 0
	v_lshl_add_u64 v[140:141], s[6:7], 0, v[112:113]
	s_mov_b32 s6, -2
	v_add_u32_e32 v112, 0, v26
	v_mov_b32_e32 v1, v0
	v_mov_b32_e32 v2, v0
	v_mov_b32_e32 v3, v0
	v_mov_b32_e32 v4, v0
	v_mov_b32_e32 v5, v0
	v_mov_b32_e32 v6, v0
	v_mov_b32_e32 v7, v0
	v_mov_b32_e32 v8, v0
	v_mov_b32_e32 v9, v0
	v_mov_b32_e32 v10, v0
	v_mov_b32_e32 v11, v0
	v_mov_b32_e32 v12, v0
	v_mov_b32_e32 v13, v0
	v_mov_b32_e32 v14, v0
	v_mov_b32_e32 v15, v0
	v_mov_b32_e32 v16, v0
	v_mov_b32_e32 v17, v0
	v_mov_b32_e32 v18, v0
	v_mov_b32_e32 v19, v0
	v_mov_b32_e32 v20, v0
	v_mov_b32_e32 v21, v0
	v_mov_b32_e32 v22, v0
	v_mov_b32_e32 v23, v0
	v_mov_b32_e32 v24, v0
	v_mov_b32_e32 v25, v0
	v_mov_b32_e32 v26, v0
	v_mov_b32_e32 v27, v0
	v_mov_b32_e32 v28, v0
	v_mov_b32_e32 v29, v0
	v_mov_b32_e32 v30, v0
	v_mov_b32_e32 v31, v0
	v_mov_b32_e32 v32, v0
	v_mov_b32_e32 v33, v0
	v_mov_b32_e32 v34, v0
	v_mov_b32_e32 v35, v0
	v_mov_b32_e32 v36, v0
	v_mov_b32_e32 v37, v0
	v_mov_b32_e32 v38, v0
	v_mov_b32_e32 v39, v0
	v_mov_b32_e32 v40, v0
	v_mov_b32_e32 v41, v0
	v_mov_b32_e32 v42, v0
	v_mov_b32_e32 v43, v0
	v_mov_b32_e32 v44, v0
	v_mov_b32_e32 v45, v0
	v_mov_b32_e32 v46, v0
	v_mov_b32_e32 v47, v0
	v_mov_b32_e32 v48, v0
	v_mov_b32_e32 v49, v0
	v_mov_b32_e32 v50, v0
	v_mov_b32_e32 v51, v0
	v_mov_b32_e32 v52, v0
	v_mov_b32_e32 v53, v0
	v_mov_b32_e32 v54, v0
	v_mov_b32_e32 v55, v0
	v_mov_b32_e32 v56, v0
	v_mov_b32_e32 v57, v0
	v_mov_b32_e32 v58, v0
	v_mov_b32_e32 v59, v0
	v_mov_b32_e32 v60, v0
	v_mov_b32_e32 v61, v0
	v_mov_b32_e32 v62, v0
	v_mov_b32_e32 v63, v0
	v_mov_b32_e32 v68, v0
	v_mov_b32_e32 v69, v0
	v_mov_b32_e32 v70, v0
	v_mov_b32_e32 v71, v0
	v_mov_b32_e32 v80, v0
	v_mov_b32_e32 v81, v0
	v_mov_b32_e32 v82, v0
	v_mov_b32_e32 v83, v0
	v_mov_b32_e32 v84, v0
	v_mov_b32_e32 v85, v0
	v_mov_b32_e32 v86, v0
	v_mov_b32_e32 v87, v0
	v_mov_b32_e32 v88, v0
	v_mov_b32_e32 v89, v0
	v_mov_b32_e32 v90, v0
	v_mov_b32_e32 v91, v0
	v_mov_b32_e32 v92, v0
	v_mov_b32_e32 v93, v0
	v_mov_b32_e32 v94, v0
	v_mov_b32_e32 v95, v0
	v_mov_b32_e32 v96, v0
	v_mov_b32_e32 v97, v0
	v_mov_b32_e32 v98, v0
	v_mov_b32_e32 v99, v0
	v_mov_b32_e32 v100, v0
	v_mov_b32_e32 v101, v0
	v_mov_b32_e32 v102, v0
	v_mov_b32_e32 v103, v0
	v_mov_b32_e32 v104, v0
	v_mov_b32_e32 v105, v0
	v_mov_b32_e32 v106, v0
	v_mov_b32_e32 v107, v0
	v_mov_b32_e32 v108, v0
	v_mov_b32_e32 v109, v0
	v_mov_b32_e32 v110, v0
	v_mov_b32_e32 v111, v0
	v_mov_b32_e32 v114, v0
	v_mov_b32_e32 v115, v0
	v_mov_b32_e32 v116, v0
	v_mov_b32_e32 v117, v0
	v_mov_b32_e32 v118, v0
	v_mov_b32_e32 v119, v0
	v_mov_b32_e32 v120, v0
	v_mov_b32_e32 v121, v0
	v_mov_b32_e32 v122, v0
	v_mov_b32_e32 v123, v0
	v_mov_b32_e32 v124, v0
	v_mov_b32_e32 v125, v0
	v_mov_b32_e32 v126, v0
	v_mov_b32_e32 v127, v0
	v_mov_b32_e32 v128, v0
	v_mov_b32_e32 v129, v0
	v_mov_b32_e32 v64, v0
	v_mov_b32_e32 v65, v0
	v_mov_b32_e32 v66, v0
	v_mov_b32_e32 v67, v0
	v_mov_b32_e32 v72, v0
	v_mov_b32_e32 v73, v0
	v_mov_b32_e32 v74, v0
	v_mov_b32_e32 v75, v0
	v_mov_b32_e32 v76, v0
	v_mov_b32_e32 v77, v0
	v_mov_b32_e32 v78, v0
	v_mov_b32_e32 v79, v0
	s_barrier

.LBB0_443:
	v_mov_b32_e32 v133, v113
	v_lshlrev_b32_e32 v0, 14, v0
	v_lshl_add_u64 v[12:13], s[4:5], 0, v[132:133]
	v_sub_u32_e32 v133, v130, v0
	v_lshlrev_b32_e32 v0, 14, v1
	v_sub_u32_e32 v141, v132, v0
	v_lshlrev_b32_e32 v0, 14, v2
	v_sub_u32_e32 v142, v134, v0
	v_lshlrev_b32_e32 v0, 14, v4
	v_mov_b32_e32 v139, v113
	v_sub_u32_e32 v140, v136, v0
	v_and_b32_e32 v0, 15, v3
	v_and_b32_e32 v1, 48, v3
	v_lshlrev_b32_e32 v3, 2, v3
	v_lshl_add_u64 v[144:145], s[2:3], 0, v[112:113]
	v_lshl_add_u64 v[164:165], s[2:3], 0, v[138:139]
	v_lshlrev_b32_e32 v0, 6, v0
	v_and_b32_e32 v3, 32, v3
	s_lshl_b32 s2, s7, 12
	v_lshl_add_u64 v[6:7], s[0:1], 0, v[112:113]
	v_or_b32_e32 v2, v0, v1
	v_bitop3_b32 v0, v0, v3, v1 bitop3:0x36
	s_and_b32 s2, s2, 0x3000
	v_lshl_add_u64 v[8:9], s[0:1], 0, v[138:139]
	v_mov_b32_e32 v131, v113
	v_or_b32_e32 v143, s2, v0
	s_add_i32 m0, s74, 0x18000
	v_lshl_add_u64 v[0:1], v[6:7], 0, s[36:37]
	s_ashr_i32 s96, s30, 31
	v_lshl_add_u64 v[10:11], s[4:5], 0, v[130:131]
	s_lshl_b32 s3, s6, 13
	global_load_lds_dwordx4 v[0:1], off
	v_lshl_add_u64 v[0:1], v[8:9], 0, s[36:37]
	s_add_i32 m0, s74, 0x1a000
	s_add_i32 s50, s74, 0x8000
	s_add_i32 s54, s74, 0xa000
	global_load_lds_dwordx4 v[0:1], off
	v_lshl_add_u64 v[0:1], v[10:11], 0, s[36:37]
	s_mov_b32 m0, s50
	s_add_u32 s2, s0, 0x18080
	v_bitop3_b32 v2, v2, s3, v3 bitop3:0xde
	global_load_lds_dwordx4 v[0:1], off
	v_lshl_add_u64 v[0:1], v[12:13], 0, s[36:37]
	s_mov_b32 m0, s54
	s_addc_u32 s3, s1, 0
	global_load_lds_dwordx4 v[0:1], off
	s_add_i32 m0, s74, 0x1c000
	v_lshl_add_u64 v[0:1], s[2:3], 0, v[112:113]
	global_load_lds_dwordx4 v[0:1], off
	v_lshl_add_u64 v[0:1], s[2:3], 0, v[138:139]
	s_add_i32 m0, s74, 0x1e000
	v_mov_b32_e32 v135, v113
	global_load_lds_dwordx4 v[0:1], off
	s_waitcnt vmcnt(8)
	s_barrier
	s_waitcnt vmcnt(6)
	v_mov_b32_e32 v0, 0
	v_mov_b32_e32 v137, v113
	s_add_i32 s55, s30, 0xffffff00
	s_or_b32 s94, s51, 0x100
	s_add_i32 s95, s30, 0xffffff80
	s_or_b32 s68, s51, 0x180
	s_mov_b32 s5, 0
	s_mov_b64 s[2:3], -1
	v_add_u32_e32 v131, 0, v2
	v_mov_b32_e32 v1, v0
	v_mov_b32_e32 v2, v0
	v_mov_b32_e32 v3, v0
	v_mov_b32_e32 v4, v0
	v_mov_b32_e32 v5, v0
	v_mov_b32_e32 v6, v0
	v_mov_b32_e32 v7, v0
	v_mov_b32_e32 v8, v0
	v_mov_b32_e32 v9, v0
	v_mov_b32_e32 v10, v0
	v_mov_b32_e32 v11, v0
	v_mov_b32_e32 v12, v0
	v_mov_b32_e32 v13, v0
	v_mov_b32_e32 v14, v0
	v_mov_b32_e32 v15, v0
	v_mov_b32_e32 v16, v0
	v_mov_b32_e32 v17, v0
	v_mov_b32_e32 v18, v0
	v_mov_b32_e32 v19, v0
	v_mov_b32_e32 v20, v0
	v_mov_b32_e32 v21, v0
	v_mov_b32_e32 v22, v0
	v_mov_b32_e32 v23, v0
	v_mov_b32_e32 v24, v0
	v_mov_b32_e32 v25, v0
	v_mov_b32_e32 v26, v0
	v_mov_b32_e32 v27, v0
	v_mov_b32_e32 v28, v0
	v_mov_b32_e32 v29, v0
	v_mov_b32_e32 v30, v0
	v_mov_b32_e32 v31, v0
	v_mov_b32_e32 v32, v0
	v_mov_b32_e32 v33, v0
	v_mov_b32_e32 v34, v0
	v_mov_b32_e32 v35, v0
	v_mov_b32_e32 v36, v0
	v_mov_b32_e32 v37, v0
	v_mov_b32_e32 v38, v0
	v_mov_b32_e32 v39, v0
	v_mov_b32_e32 v40, v0
	v_mov_b32_e32 v41, v0
	v_mov_b32_e32 v42, v0
	v_mov_b32_e32 v43, v0
	v_mov_b32_e32 v44, v0
	v_mov_b32_e32 v45, v0
	v_mov_b32_e32 v46, v0
	v_mov_b32_e32 v47, v0
	v_mov_b32_e32 v64, v0
	v_mov_b32_e32 v65, v0
	v_mov_b32_e32 v66, v0
	v_mov_b32_e32 v67, v0
	v_mov_b32_e32 v80, v0
	v_mov_b32_e32 v81, v0
	v_mov_b32_e32 v82, v0
	v_mov_b32_e32 v83, v0
	v_mov_b32_e32 v96, v0
	v_mov_b32_e32 v97, v0
	v_mov_b32_e32 v98, v0
	v_mov_b32_e32 v99, v0
	v_mov_b32_e32 v100, v0
	v_mov_b32_e32 v101, v0
	v_mov_b32_e32 v102, v0
	v_mov_b32_e32 v103, v0
	v_mov_b32_e32 v104, v0
	v_mov_b32_e32 v105, v0
	v_mov_b32_e32 v106, v0
	v_mov_b32_e32 v107, v0
	v_mov_b32_e32 v108, v0
	v_mov_b32_e32 v109, v0
	v_mov_b32_e32 v110, v0
	v_mov_b32_e32 v111, v0
	v_mov_b32_e32 v114, v0
	v_mov_b32_e32 v115, v0
	v_mov_b32_e32 v116, v0
	v_mov_b32_e32 v117, v0
	v_mov_b32_e32 v118, v0
	v_mov_b32_e32 v119, v0
	v_mov_b32_e32 v120, v0
	v_mov_b32_e32 v121, v0
	v_mov_b32_e32 v122, v0
	v_mov_b32_e32 v123, v0
	v_mov_b32_e32 v124, v0
	v_mov_b32_e32 v125, v0
	v_mov_b32_e32 v126, v0
	v_mov_b32_e32 v127, v0
	v_mov_b32_e32 v128, v0
	v_mov_b32_e32 v129, v0
	v_mov_b32_e32 v48, v0
	v_mov_b32_e32 v49, v0
	v_mov_b32_e32 v50, v0
	v_mov_b32_e32 v51, v0
	v_mov_b32_e32 v52, v0
	v_mov_b32_e32 v53, v0
	v_mov_b32_e32 v54, v0
	v_mov_b32_e32 v55, v0
	v_mov_b32_e32 v56, v0
	v_mov_b32_e32 v57, v0
	v_mov_b32_e32 v58, v0
	v_mov_b32_e32 v59, v0
	v_mov_b32_e32 v60, v0
	v_mov_b32_e32 v61, v0
	v_mov_b32_e32 v62, v0
	v_mov_b32_e32 v63, v0
	v_mov_b32_e32 v68, v0
	v_mov_b32_e32 v69, v0
	v_mov_b32_e32 v70, v0
	v_mov_b32_e32 v71, v0
	v_mov_b32_e32 v72, v0
	v_mov_b32_e32 v73, v0
	v_mov_b32_e32 v74, v0
	v_mov_b32_e32 v75, v0
	v_mov_b32_e32 v76, v0
	v_mov_b32_e32 v77, v0
	v_mov_b32_e32 v78, v0
	v_mov_b32_e32 v79, v0
	v_mov_b32_e32 v84, v0
	v_mov_b32_e32 v85, v0
	v_mov_b32_e32 v86, v0
	v_mov_b32_e32 v87, v0
	v_mov_b32_e32 v88, v0
	v_mov_b32_e32 v89, v0
	v_mov_b32_e32 v90, v0
	v_mov_b32_e32 v91, v0
	v_mov_b32_e32 v92, v0
	v_mov_b32_e32 v93, v0
	v_mov_b32_e32 v94, v0
	v_mov_b32_e32 v95, v0
	s_barrier

.LBB0_555:
	s_lshl_b32 s25, s25, 12
	s_add_i32 m0, s31, 0x18000
	v_lshl_add_u64 v[8:9], v[8:9], 0, s[36:37]
	s_lshl_b32 s24, s24, 13
	s_and_b32 s25, s25, 0x3000
	global_load_lds_dwordx4 v[8:9], off
	v_lshl_add_u64 v[6:7], v[6:7], 0, s[36:37]
	s_add_i32 m0, s31, 0x1a000
	s_add_i32 s46, s31, 0x8000
	s_add_i32 s47, s31, 0xa000
	global_load_lds_dwordx4 v[6:7], off
	v_lshl_add_u64 v[4:5], v[4:5], 0, s[36:37]
	s_mov_b32 m0, s46
	s_add_u32 s8, s8, 0x40080
	global_load_lds_dwordx4 v[4:5], off
	v_lshl_add_u64 v[2:3], v[2:3], 0, s[36:37]
	s_mov_b32 m0, s47
	s_addc_u32 s9, s9, 0
	global_load_lds_dwordx4 v[2:3], off
	s_add_i32 m0, s31, 0x1c000
	v_lshl_add_u64 v[2:3], s[8:9], 0, v[112:113]
	global_load_lds_dwordx4 v[2:3], off
	v_lshl_add_u64 v[0:1], s[8:9], 0, v[0:1]
	s_add_i32 m0, s31, 0x1e000
	v_readlane_b32 s8, v252, 11
	global_load_lds_dwordx4 v[0:1], off
	s_waitcnt vmcnt(8)
	s_barrier
	v_lshlrev_b32_e32 v0, 13, v18
	v_and_b32_e32 v0, 0x7fffc000, v0
	v_lshl_add_u32 v0, v19, 10, v0
	v_or_b32_e32 v0, v0, v20
	v_add_lshl_u32 v112, v0, v21, 1
	v_lshlrev_b32_e32 v0, 13, v22
	v_and_b32_e32 v0, 0x7fffc000, v0
	v_readlane_b32 s9, v252, 12
	s_add_u32 s6, s8, s6
	v_lshl_add_u32 v0, v23, 10, v0
	s_addc_u32 s7, s9, s7
	v_or_b32_e32 v0, v0, v24
	v_lshl_add_u64 v[134:135], s[6:7], 0, v[112:113]
	v_add_lshl_u32 v112, v0, v25, 1
	v_lshlrev_b32_e32 v0, 13, v10
	v_and_b32_e32 v0, 0x7fffc000, v0
	v_lshl_add_u32 v0, v11, 10, v0
	v_or_b32_e32 v0, v0, v12
	v_lshl_add_u64 v[136:137], s[6:7], 0, v[112:113]
	v_add_lshl_u32 v112, v0, v13, 1
	v_lshlrev_b32_e32 v0, 13, v14
	v_and_b32_e32 v27, 15, v26
	v_and_b32_e32 v0, 0x7fffc000, v0
	v_and_b32_e32 v28, 48, v26
	v_lshlrev_b32_e32 v27, 6, v27
	v_lshlrev_b32_e32 v26, 2, v26
	v_lshl_add_u32 v0, v15, 10, v0
	v_or_b32_e32 v29, v27, v28
	v_and_b32_e32 v26, 32, v26
	s_waitcnt vmcnt(6)
	v_or_b32_e32 v0, v0, v16
	v_bitop3_b32 v27, v27, v26, v28 bitop3:0x36
	v_bitop3_b32 v26, v29, s24, v26 bitop3:0xde
	v_lshl_add_u64 v[138:139], s[4:5], 0, v[112:113]
	v_add_lshl_u32 v112, v0, v17, 1
	v_mov_b32_e32 v0, 0
	v_or_b32_e32 v142, s25, v27
	v_lshl_add_u64 v[140:141], s[4:5], 0, v[112:113]
	s_mov_b32 s4, -2
	v_add_u32_e32 v112, 0, v26
	v_mov_b32_e32 v1, v0
	v_mov_b32_e32 v2, v0
	v_mov_b32_e32 v3, v0
	v_mov_b32_e32 v4, v0
	v_mov_b32_e32 v5, v0
	v_mov_b32_e32 v6, v0
	v_mov_b32_e32 v7, v0
	v_mov_b32_e32 v8, v0
	v_mov_b32_e32 v9, v0
	v_mov_b32_e32 v10, v0
	v_mov_b32_e32 v11, v0
	v_mov_b32_e32 v12, v0
	v_mov_b32_e32 v13, v0
	v_mov_b32_e32 v14, v0
	v_mov_b32_e32 v15, v0
	v_mov_b32_e32 v16, v0
	v_mov_b32_e32 v17, v0
	v_mov_b32_e32 v18, v0
	v_mov_b32_e32 v19, v0
	v_mov_b32_e32 v20, v0
	v_mov_b32_e32 v21, v0
	v_mov_b32_e32 v22, v0
	v_mov_b32_e32 v23, v0
	v_mov_b32_e32 v24, v0
	v_mov_b32_e32 v25, v0
	v_mov_b32_e32 v26, v0
	v_mov_b32_e32 v27, v0
	v_mov_b32_e32 v28, v0
	v_mov_b32_e32 v29, v0
	v_mov_b32_e32 v30, v0
	v_mov_b32_e32 v31, v0
	v_mov_b32_e32 v32, v0
	v_mov_b32_e32 v33, v0
	v_mov_b32_e32 v34, v0
	v_mov_b32_e32 v35, v0
	v_mov_b32_e32 v36, v0
	v_mov_b32_e32 v37, v0
	v_mov_b32_e32 v38, v0
	v_mov_b32_e32 v39, v0
	v_mov_b32_e32 v40, v0
	v_mov_b32_e32 v41, v0
	v_mov_b32_e32 v42, v0
	v_mov_b32_e32 v43, v0
	v_mov_b32_e32 v44, v0
	v_mov_b32_e32 v45, v0
	v_mov_b32_e32 v46, v0
	v_mov_b32_e32 v47, v0
	v_mov_b32_e32 v48, v0
	v_mov_b32_e32 v49, v0
	v_mov_b32_e32 v50, v0
	v_mov_b32_e32 v51, v0
	v_mov_b32_e32 v52, v0
	v_mov_b32_e32 v53, v0
	v_mov_b32_e32 v54, v0
	v_mov_b32_e32 v55, v0
	v_mov_b32_e32 v56, v0
	v_mov_b32_e32 v57, v0
	v_mov_b32_e32 v58, v0
	v_mov_b32_e32 v59, v0
	v_mov_b32_e32 v60, v0
	v_mov_b32_e32 v61, v0
	v_mov_b32_e32 v62, v0
	v_mov_b32_e32 v63, v0
	v_mov_b32_e32 v68, v0
	v_mov_b32_e32 v69, v0
	v_mov_b32_e32 v70, v0
	v_mov_b32_e32 v71, v0
	v_mov_b32_e32 v80, v0
	v_mov_b32_e32 v81, v0
	v_mov_b32_e32 v82, v0
	v_mov_b32_e32 v83, v0
	v_mov_b32_e32 v84, v0
	v_mov_b32_e32 v85, v0
	v_mov_b32_e32 v86, v0
	v_mov_b32_e32 v87, v0
	v_mov_b32_e32 v88, v0
	v_mov_b32_e32 v89, v0
	v_mov_b32_e32 v90, v0
	v_mov_b32_e32 v91, v0
	v_mov_b32_e32 v92, v0
	v_mov_b32_e32 v93, v0
	v_mov_b32_e32 v94, v0
	v_mov_b32_e32 v95, v0
	v_mov_b32_e32 v96, v0
	v_mov_b32_e32 v97, v0
	v_mov_b32_e32 v98, v0
	v_mov_b32_e32 v99, v0
	v_mov_b32_e32 v100, v0
	v_mov_b32_e32 v101, v0
	v_mov_b32_e32 v102, v0
	v_mov_b32_e32 v103, v0
	v_mov_b32_e32 v104, v0
	v_mov_b32_e32 v105, v0
	v_mov_b32_e32 v106, v0
	v_mov_b32_e32 v107, v0
	v_mov_b32_e32 v108, v0
	v_mov_b32_e32 v109, v0
	v_mov_b32_e32 v110, v0
	v_mov_b32_e32 v111, v0
	v_mov_b32_e32 v114, v0
	v_mov_b32_e32 v115, v0
	v_mov_b32_e32 v116, v0
	v_mov_b32_e32 v117, v0
	v_mov_b32_e32 v118, v0
	v_mov_b32_e32 v119, v0
	v_mov_b32_e32 v120, v0
	v_mov_b32_e32 v121, v0
	v_mov_b32_e32 v122, v0
	v_mov_b32_e32 v123, v0
	v_mov_b32_e32 v124, v0
	v_mov_b32_e32 v125, v0
	v_mov_b32_e32 v126, v0
	v_mov_b32_e32 v127, v0
	v_mov_b32_e32 v128, v0
	v_mov_b32_e32 v129, v0
	v_mov_b32_e32 v64, v0
	v_mov_b32_e32 v65, v0
	v_mov_b32_e32 v66, v0
	v_mov_b32_e32 v67, v0
	v_mov_b32_e32 v72, v0
	v_mov_b32_e32 v73, v0
	v_mov_b32_e32 v74, v0
	v_mov_b32_e32 v75, v0
	v_mov_b32_e32 v76, v0
	v_mov_b32_e32 v77, v0
	v_mov_b32_e32 v78, v0
	v_mov_b32_e32 v79, v0
	s_barrier

.LBB0_821:
	v_or_b32_e32 v16, s0, v7
	v_and_b32_e32 v6, 48, v6
	v_lshlrev_b32_e32 v17, 6, v16
	s_movk_i32 s0, 0x3c0
	v_lshlrev_b32_e32 v16, 2, v16
	v_and_or_b32 v17, v17, s0, v6
	s_lshl_b32 s0, s2, 13
	v_and_b32_e32 v16, 32, v16
	v_mov_b32_e32 v131, v113
	v_bitop3_b32 v16, v17, s0, v16 bitop3:0xde
	s_lshl_b32 s0, s3, 12
	v_lshlrev_b32_e32 v7, 6, v7
	v_and_b32_e32 v17, 32, v112
	v_lshl_add_u64 v[8:9], s[12:13], 0, v[130:131]
	v_mov_b32_e32 v133, v113
	s_and_b32 s0, s0, 0x3000
	v_bitop3_b32 v6, v7, v17, v6 bitop3:0x36
	v_lshl_add_u64 v[10:11], s[12:13], 0, v[132:133]
	v_or_b32_e32 v192, s0, v6
	s_add_i32 m0, s14, 0x18000
	v_lshl_add_u64 v[6:7], v[8:9], 0, s[36:37]
	v_lshl_add_u64 v[12:13], s[50:51], 0, v[130:131]
	global_load_lds_dwordx4 v[6:7], off
	v_lshl_add_u64 v[6:7], v[10:11], 0, s[36:37]
	s_add_i32 m0, s14, 0x1a000
	s_add_i32 s33, s14, 0x8000
	s_add_i32 s46, s14, 0xa000
	v_lshl_add_u64 v[14:15], s[50:51], 0, v[132:133]
	global_load_lds_dwordx4 v[6:7], off
	v_lshl_add_u64 v[6:7], v[12:13], 0, s[36:37]
	s_mov_b32 m0, s33
	s_add_u32 s0, s12, 0x40080
	global_load_lds_dwordx4 v[6:7], off
	v_lshl_add_u64 v[6:7], v[14:15], 0, s[36:37]
	s_mov_b32 m0, s46
	s_addc_u32 s1, s13, 0
	global_load_lds_dwordx4 v[6:7], off
	s_add_i32 m0, s14, 0x1c000
	v_lshl_add_u64 v[6:7], s[0:1], 0, v[130:131]
	global_load_lds_dwordx4 v[6:7], off
	v_lshl_add_u64 v[6:7], s[0:1], 0, v[132:133]
	s_add_i32 m0, s14, 0x1e000
	s_cmpk_lt_u32 s6, 0x100
	global_load_lds_dwordx4 v[6:7], off
	s_waitcnt vmcnt(8)
	s_barrier
	v_lshlrev_b32_e32 v6, 14, v0
	v_and_b32_e32 v6, 0xffff8000, v6
	v_lshl_add_u32 v1, v1, 11, v6
	v_and_b32_e32 v0, 1, v0
	v_lshl_or_b32 v0, v0, 6, v1
	v_lshl_add_u32 v138, v2, 1, v0
	v_lshlrev_b32_e32 v0, 14, v3
	v_and_b32_e32 v0, 0xffff8000, v0
	s_waitcnt vmcnt(6)
	v_lshl_add_u32 v0, v4, 11, v0
	v_and_b32_e32 v1, 1, v3
	v_lshl_or_b32 v0, v1, 6, v0
	s_cselect_b64 s[8:9], -1, 0
	v_mov_b32_e32 v139, v113
	v_lshl_add_u32 v140, v5, 1, v0
	v_mov_b32_e32 v141, v113
	s_mov_b32 s47, 0
	v_add_u32_e32 v193, 0, v16
	s_mov_b32 s97, 0x8000
	s_barrier
	s_branch .LBB0_824

.LBB0_1319:
	v_readlane_b32 s2, v254, 59
	v_readlane_b32 s3, v254, 60
	v_lshrrev_b32_e32 v228, 6, v180
	v_mul_u32_u24_e32 v228, 0x480, v228
	v_add_u32_e32 v228, 0x20200, v228
	v_mul_u32_u24_e32 v229, 144, v176
	v_lshl_add_u32 v229, v172, 1, v229
	v_add_u32_e32 v229, v229, v228
	v_lshrrev_b32_e32 v232, 3, v172
	v_add_u32_e32 v232, v232, v176
	v_and_b32_e32 v231, 7, v172
	v_mul_u32_u24_e32 v230, 144, v232
	v_lshl_add_u32 v230, v231, 4, v230
	v_add_u32_e32 v230, v230, v228
	v_add_u32_e32 v232, s46, v232
	v_lshlrev_b32_e32 v232, 11, v232
	v_lshl_add_u32 v232, v231, 4, v232
	v_mov_b32_e32 v231, s0
	v_lshl_add_u32 v232, v231, 7, v232
	v_cvt_pk_bf16_f32 v206, v64, v113
	v_cvt_pk_bf16_f32 v207, v80, v113
	ds_write_b16 v229, v206
	ds_write_b16 v229, v207 offset:64
	v_cvt_pk_bf16_f32 v208, v65, v113
	v_cvt_pk_bf16_f32 v209, v81, v113
	ds_write_b16 v229, v208 offset:144
	ds_write_b16 v229, v209 offset:208
	v_cvt_pk_bf16_f32 v206, v66, v113
	v_cvt_pk_bf16_f32 v207, v82, v113
	ds_write_b16 v229, v206 offset:288
	ds_write_b16 v229, v207 offset:352
	v_cvt_pk_bf16_f32 v208, v67, v113
	v_cvt_pk_bf16_f32 v209, v83, v113
	ds_write_b16 v229, v208 offset:432
	ds_write_b16 v229, v209 offset:496
	ds_read_b128 v[212:215], v230
	v_cvt_pk_bf16_f32 v206, v68, v113
	v_cvt_pk_bf16_f32 v207, v84, v113
	ds_write_b16 v229, v206
	ds_write_b16 v229, v207 offset:64
	v_cvt_pk_bf16_f32 v208, v69, v113
	v_cvt_pk_bf16_f32 v209, v85, v113
	ds_write_b16 v229, v208 offset:144
	ds_write_b16 v229, v209 offset:208
	v_cvt_pk_bf16_f32 v206, v70, v113
	v_cvt_pk_bf16_f32 v207, v86, v113
	ds_write_b16 v229, v206 offset:288
	ds_write_b16 v229, v207 offset:352
	v_cvt_pk_bf16_f32 v208, v71, v113
	v_cvt_pk_bf16_f32 v209, v87, v113
	ds_write_b16 v229, v208 offset:432
	ds_write_b16 v229, v209 offset:496
	ds_read_b128 v[216:219], v230
	s_waitcnt lgkmcnt(9)
	global_store_dwordx4 v232, v[212:215], s[2:3]
	v_cvt_pk_bf16_f32 v206, v72, v113
	v_cvt_pk_bf16_f32 v207, v88, v113
	ds_write_b16 v229, v206
	ds_write_b16 v229, v207 offset:64
	v_cvt_pk_bf16_f32 v208, v73, v113
	v_cvt_pk_bf16_f32 v209, v89, v113
	ds_write_b16 v229, v208 offset:144
	ds_write_b16 v229, v209 offset:208
	v_cvt_pk_bf16_f32 v206, v74, v113
	v_cvt_pk_bf16_f32 v207, v90, v113
	ds_write_b16 v229, v206 offset:288
	ds_write_b16 v229, v207 offset:352
	v_cvt_pk_bf16_f32 v208, v75, v113
	v_cvt_pk_bf16_f32 v209, v91, v113
	ds_write_b16 v229, v208 offset:432
	ds_write_b16 v229, v209 offset:496
	ds_read_b128 v[220:223], v230
	s_waitcnt lgkmcnt(9)
	v_add_u32_e32 v232, 0x4000, v232
	global_store_dwordx4 v232, v[216:219], s[2:3]
	v_cvt_pk_bf16_f32 v206, v76, v113
	v_cvt_pk_bf16_f32 v207, v92, v113
	ds_write_b16 v229, v206
	ds_write_b16 v229, v207 offset:64
	v_cvt_pk_bf16_f32 v208, v77, v113
	v_cvt_pk_bf16_f32 v209, v93, v113
	ds_write_b16 v229, v208 offset:144
	ds_write_b16 v229, v209 offset:208
	v_cvt_pk_bf16_f32 v206, v78, v113
	v_cvt_pk_bf16_f32 v207, v94, v113
	ds_write_b16 v229, v206 offset:288
	ds_write_b16 v229, v207 offset:352
	v_cvt_pk_bf16_f32 v208, v79, v113
	v_cvt_pk_bf16_f32 v209, v95, v113
	ds_write_b16 v229, v208 offset:432
	ds_write_b16 v229, v209 offset:496
	ds_read_b128 v[224:227], v230
	s_waitcnt lgkmcnt(9)
	v_add_u32_e32 v232, 0x4000, v232
	global_store_dwordx4 v232, v[220:223], s[2:3]
	s_waitcnt lgkmcnt(0)
	v_add_u32_e32 v232, 0x4000, v232
	global_store_dwordx4 v232, v[224:227], s[2:3]
	s_waitcnt vmcnt(4)
	s_branch .Lmy_att_top2

.LBB0_1470:
	v_and_b32_e32 v27, 15, v26
	v_and_b32_e32 v28, 48, v26
	v_lshlrev_b32_e32 v27, 6, v27
	v_lshlrev_b32_e32 v26, 2, v26
	s_lshl_b32 s25, s25, 12
	s_add_i32 m0, s97, 0x18000
	v_lshl_add_u64 v[2:3], v[2:3], 0, s[36:37]
	v_or_b32_e32 v29, v27, v28
	v_and_b32_e32 v26, 32, v26
	s_lshl_b32 s24, s24, 13
	s_and_b32 s25, s25, 0x3000
	global_load_lds_dwordx4 v[2:3], off
	v_lshl_add_u64 v[2:3], v[4:5], 0, s[36:37]
	s_add_i32 m0, s97, 0x1a000
	s_add_i32 s54, s97, 0x8000
	s_add_i32 s55, s97, 0xa000
	v_bitop3_b32 v27, v27, v26, v28 bitop3:0x36
	v_bitop3_b32 v26, v29, s24, v26 bitop3:0xde
	global_load_lds_dwordx4 v[2:3], off
	v_lshl_add_u64 v[2:3], v[6:7], 0, s[36:37]
	s_mov_b32 m0, s54
	s_add_u32 s24, s48, 0x40080
	v_or_b32_e32 v142, s25, v27
	global_load_lds_dwordx4 v[2:3], off
	v_lshl_add_u64 v[2:3], v[8:9], 0, s[36:37]
	s_mov_b32 m0, s55
	s_addc_u32 s25, s49, 0
	global_load_lds_dwordx4 v[2:3], off
	s_add_i32 m0, s97, 0x1c000
	v_lshl_add_u64 v[2:3], s[24:25], 0, v[112:113]
	global_load_lds_dwordx4 v[2:3], off
	v_lshl_add_u64 v[0:1], s[24:25], 0, v[0:1]
	s_add_i32 m0, s97, 0x1e000
	s_add_i32 s48, s10, -2
	global_load_lds_dwordx4 v[0:1], off
	s_waitcnt vmcnt(8)
	s_barrier
	v_lshlrev_b32_e32 v0, 13, v18
	v_and_b32_e32 v0, 0x7fffc000, v0
	v_lshl_add_u32 v0, v19, 10, v0
	v_or_b32_e32 v0, v0, v20
	v_add_lshl_u32 v112, v0, v22, 1
	v_lshlrev_b32_e32 v0, 13, v21
	v_and_b32_e32 v0, 0x7fffc000, v0
	s_add_u32 s24, s31, s38
	v_lshl_add_u32 v0, v23, 10, v0
	s_addc_u32 s25, s47, s39
	v_or_b32_e32 v0, v0, v24
	v_lshl_add_u64 v[134:135], s[24:25], 0, v[112:113]
	v_add_lshl_u32 v112, v0, v25, 1
	v_lshlrev_b32_e32 v0, 13, v10
	v_and_b32_e32 v0, 0x7fffc000, v0
	v_lshl_add_u32 v0, v11, 10, v0
	v_or_b32_e32 v0, v0, v12
	v_lshl_add_u64 v[136:137], s[24:25], 0, v[112:113]
	v_add_lshl_u32 v112, v0, v13, 1
	v_lshlrev_b32_e32 v0, 13, v14
	v_and_b32_e32 v0, 0x7fffc000, v0
	s_add_u32 s12, s78, s12
	v_lshl_add_u32 v0, v15, 10, v0
	s_waitcnt vmcnt(6)
	s_addc_u32 s13, s79, s13
	v_or_b32_e32 v0, v0, v16
	v_lshl_add_u64 v[138:139], s[12:13], 0, v[112:113]
	v_add_lshl_u32 v112, v0, v17, 1
	v_mov_b32_e32 v0, 0
	v_lshl_add_u64 v[140:141], s[12:13], 0, v[112:113]
	s_mov_b32 s12, 0
	v_add_u32_e32 v112, 0, v26
	v_mov_b32_e32 v1, v0
	v_mov_b32_e32 v2, v0
	v_mov_b32_e32 v3, v0
	v_mov_b32_e32 v4, v0
	v_mov_b32_e32 v5, v0
	v_mov_b32_e32 v6, v0
	v_mov_b32_e32 v7, v0
	v_mov_b32_e32 v8, v0
	v_mov_b32_e32 v9, v0
	v_mov_b32_e32 v10, v0
	v_mov_b32_e32 v11, v0
	v_mov_b32_e32 v12, v0
	v_mov_b32_e32 v13, v0
	v_mov_b32_e32 v14, v0
	v_mov_b32_e32 v15, v0
	v_mov_b32_e32 v16, v0
	v_mov_b32_e32 v17, v0
	v_mov_b32_e32 v18, v0
	v_mov_b32_e32 v19, v0
	v_mov_b32_e32 v20, v0
	v_mov_b32_e32 v21, v0
	v_mov_b32_e32 v22, v0
	v_mov_b32_e32 v23, v0
	v_mov_b32_e32 v24, v0
	v_mov_b32_e32 v25, v0
	v_mov_b32_e32 v26, v0
	v_mov_b32_e32 v27, v0
	v_mov_b32_e32 v28, v0
	v_mov_b32_e32 v29, v0
	v_mov_b32_e32 v30, v0
	v_mov_b32_e32 v31, v0
	v_mov_b32_e32 v32, v0
	v_mov_b32_e32 v33, v0
	v_mov_b32_e32 v34, v0
	v_mov_b32_e32 v35, v0
	v_mov_b32_e32 v36, v0
	v_mov_b32_e32 v37, v0
	v_mov_b32_e32 v38, v0
	v_mov_b32_e32 v39, v0
	v_mov_b32_e32 v40, v0
	v_mov_b32_e32 v41, v0
	v_mov_b32_e32 v42, v0
	v_mov_b32_e32 v43, v0
	v_mov_b32_e32 v44, v0
	v_mov_b32_e32 v45, v0
	v_mov_b32_e32 v46, v0
	v_mov_b32_e32 v47, v0
	v_mov_b32_e32 v48, v0
	v_mov_b32_e32 v49, v0
	v_mov_b32_e32 v50, v0
	v_mov_b32_e32 v51, v0
	v_mov_b32_e32 v52, v0
	v_mov_b32_e32 v53, v0
	v_mov_b32_e32 v54, v0
	v_mov_b32_e32 v55, v0
	v_mov_b32_e32 v56, v0
	v_mov_b32_e32 v57, v0
	v_mov_b32_e32 v58, v0
	v_mov_b32_e32 v59, v0
	v_mov_b32_e32 v60, v0
	v_mov_b32_e32 v61, v0
	v_mov_b32_e32 v62, v0
	v_mov_b32_e32 v63, v0
	v_mov_b32_e32 v68, v0
	v_mov_b32_e32 v69, v0
	v_mov_b32_e32 v70, v0
	v_mov_b32_e32 v71, v0
	v_mov_b32_e32 v80, v0
	v_mov_b32_e32 v81, v0
	v_mov_b32_e32 v82, v0
	v_mov_b32_e32 v83, v0
	v_mov_b32_e32 v84, v0
	v_mov_b32_e32 v85, v0
	v_mov_b32_e32 v86, v0
	v_mov_b32_e32 v87, v0
	v_mov_b32_e32 v88, v0
	v_mov_b32_e32 v89, v0
	v_mov_b32_e32 v90, v0
	v_mov_b32_e32 v91, v0
	v_mov_b32_e32 v92, v0
	v_mov_b32_e32 v93, v0
	v_mov_b32_e32 v94, v0
	v_mov_b32_e32 v95, v0
	v_mov_b32_e32 v96, v0
	v_mov_b32_e32 v97, v0
	v_mov_b32_e32 v98, v0
	v_mov_b32_e32 v99, v0
	v_mov_b32_e32 v100, v0
	v_mov_b32_e32 v101, v0
	v_mov_b32_e32 v102, v0
	v_mov_b32_e32 v103, v0
	v_mov_b32_e32 v104, v0
	v_mov_b32_e32 v105, v0
	v_mov_b32_e32 v106, v0
	v_mov_b32_e32 v107, v0
	v_mov_b32_e32 v108, v0
	v_mov_b32_e32 v109, v0
	v_mov_b32_e32 v110, v0
	v_mov_b32_e32 v111, v0
	v_mov_b32_e32 v114, v0
	v_mov_b32_e32 v115, v0
	v_mov_b32_e32 v116, v0
	v_mov_b32_e32 v117, v0
	v_mov_b32_e32 v118, v0
	v_mov_b32_e32 v119, v0
	v_mov_b32_e32 v120, v0
	v_mov_b32_e32 v121, v0
	v_mov_b32_e32 v122, v0
	v_mov_b32_e32 v123, v0
	v_mov_b32_e32 v124, v0
	v_mov_b32_e32 v125, v0
	v_mov_b32_e32 v126, v0
	v_mov_b32_e32 v127, v0
	v_mov_b32_e32 v128, v0
	v_mov_b32_e32 v129, v0
	v_mov_b32_e32 v64, v0
	v_mov_b32_e32 v65, v0
	v_mov_b32_e32 v66, v0
	v_mov_b32_e32 v67, v0
	v_mov_b32_e32 v72, v0
	v_mov_b32_e32 v73, v0
	v_mov_b32_e32 v74, v0
	v_mov_b32_e32 v75, v0
	v_mov_b32_e32 v76, v0
	v_mov_b32_e32 v77, v0
	v_mov_b32_e32 v78, v0
	v_mov_b32_e32 v79, v0
	s_barrier

.LBB0_1746:
	s_lshl_b32 s3, s0, 13
	s_lshl_b32 s0, s1, 12
	s_add_i32 m0, s33, 0x18000
	v_lshl_add_u64 v[8:9], v[8:9], 0, s[36:37]
	s_and_b32 s8, s0, 0x3000
	global_load_lds_dwordx4 v[8:9], off
	v_lshl_add_u64 v[6:7], v[6:7], 0, s[36:37]
	s_add_i32 m0, s33, 0x1a000
	s_add_i32 s0, s33, 0x8000
	s_add_i32 s1, s33, 0xa000
	global_load_lds_dwordx4 v[6:7], off
	v_lshl_add_u64 v[2:3], v[2:3], 0, s[36:37]
	s_mov_b32 m0, s0
	s_add_u32 s6, s12, 0x40080
	global_load_lds_dwordx4 v[2:3], off
	v_lshl_add_u64 v[2:3], v[4:5], 0, s[36:37]
	s_mov_b32 m0, s1
	s_addc_u32 s7, s13, 0
	global_load_lds_dwordx4 v[2:3], off
	s_add_i32 m0, s33, 0x1c000
	v_lshl_add_u64 v[2:3], s[6:7], 0, v[112:113]
	global_load_lds_dwordx4 v[2:3], off
	v_lshl_add_u64 v[2:3], s[6:7], 0, v[130:131]
	s_add_i32 m0, s33, 0x1e000
	v_or_b32_e32 v1, s2, v17
	global_load_lds_dwordx4 v[2:3], off
	s_waitcnt vmcnt(8)
	s_barrier
	v_and_b32_e32 v2, 48, v10
	v_lshlrev_b32_e32 v3, 6, v1
	s_movk_i32 s2, 0x3c0
	v_lshlrev_b32_e32 v1, 2, v1
	v_and_or_b32 v3, v3, s2, v2
	v_and_b32_e32 v1, 32, v1
	v_bitop3_b32 v1, v3, s3, v1 bitop3:0xde
	v_lshlrev_b32_e32 v3, 6, v17
	v_and_b32_e32 v0, 32, v0
	v_bitop3_b32 v0, v3, v0, v2 bitop3:0x36
	v_or_b32_e32 v135, s8, v0
	v_lshlrev_b32_e32 v0, 14, v11
	v_and_b32_e32 v0, 0xffff8000, v0
	v_lshl_add_u32 v0, v12, 11, v0
	v_and_b32_e32 v2, 1, v11
	v_lshl_or_b32 v0, v2, 6, v0
	v_lshl_add_u32 v136, v13, 1, v0
	v_lshlrev_b32_e32 v0, 14, v14
	v_and_b32_e32 v0, 0xffff8000, v0
	s_waitcnt vmcnt(6)
	v_lshl_add_u32 v0, v15, 11, v0
	v_and_b32_e32 v2, 1, v14
	s_cmpk_lt_u32 s5, 0x100
	v_lshl_or_b32 v0, v2, 6, v0
	s_sext_i32_i16 s31, s4
	s_cselect_b64 s[4:5], -1, 0
	v_mov_b32_e32 v137, v113
	v_lshl_add_u32 v138, v16, 1, v0
	v_mov_b32_e32 v139, v113
	s_mov_b32 s30, 0
	v_add_u32_e32 v141, 0, v1
	s_barrier
	s_branch .LBB0_1749

.LBB0_1823:
	v_and_b32_e32 v27, 15, v26
	v_and_b32_e32 v28, 48, v26
	v_lshlrev_b32_e32 v26, 2, v26
	v_lshlrev_b32_e32 v27, 6, v27
	v_and_b32_e32 v26, 32, v26
	s_lshl_b32 s54, s54, 12
	v_or_b32_e32 v29, v27, v28
	v_bitop3_b32 v27, v27, v26, v28 bitop3:0x36
	s_and_b32 s54, s54, 0x3000
	s_add_i32 m0, s49, 0x18000
	v_lshl_add_u64 v[2:3], v[2:3], 0, s[36:37]
	s_lshl_b32 s52, s52, 13
	s_waitcnt vmcnt(0)
	v_or_b32_e32 v142, s54, v27
	global_load_lds_dwordx4 v[2:3], off
	v_lshl_add_u64 v[2:3], v[4:5], 0, s[36:37]
	s_add_i32 m0, s49, 0x1a000
	s_add_i32 s54, s49, 0x8000
	s_add_i32 s55, s49, 0xa000
	global_load_lds_dwordx4 v[2:3], off
	v_lshl_add_u64 v[2:3], v[6:7], 0, s[36:37]
	s_mov_b32 m0, s54
	s_add_u32 s8, s8, 0xb0080
	global_load_lds_dwordx4 v[2:3], off
	v_lshl_add_u64 v[2:3], v[8:9], 0, s[36:37]
	s_mov_b32 m0, s55
	s_addc_u32 s9, s9, 0
	global_load_lds_dwordx4 v[2:3], off
	s_add_i32 m0, s49, 0x1c000
	v_lshl_add_u64 v[2:3], s[8:9], 0, v[112:113]
	global_load_lds_dwordx4 v[2:3], off
	v_lshl_add_u64 v[0:1], s[8:9], 0, v[0:1]
	s_add_i32 m0, s49, 0x1e000
	s_add_i32 s8, s10, -2
	global_load_lds_dwordx4 v[0:1], off
	s_waitcnt vmcnt(8)
	s_barrier
	v_readlane_b32 s56, v252, 9
	v_readlane_b32 s57, v252, 10
	s_add_u32 s9, s56, s53
	s_addc_u32 s53, s57, s58
	s_movk_i32 s56, 0xb00
	v_bitop3_b32 v26, v29, s52, v26 bitop3:0xde
	s_add_u32 s52, s9, s6
	v_lshrrev_b32_e32 v1, 1, v18
	v_mul_lo_u32 v0, v20, s56
	s_mov_b32 s9, 0xb000
	v_mad_u64_u32 v[0:1], s[58:59], v1, s9, v[0:1]
	v_or_b32_e32 v0, v0, v19
	v_add_lshl_u32 v112, v0, v21, 1
	v_lshrrev_b32_e32 v1, 1, v22
	v_mul_lo_u32 v0, v23, s56
	v_mad_u64_u32 v[0:1], s[58:59], v1, s9, v[0:1]
	s_addc_u32 s53, s53, s7
	v_or_b32_e32 v0, v0, v24
	v_lshl_add_u64 v[134:135], s[52:53], 0, v[112:113]
	v_add_lshl_u32 v112, v0, v25, 1
	s_add_u32 s6, s24, s6
	v_lshrrev_b32_e32 v1, 1, v10
	v_mul_lo_u32 v0, v11, s56
	s_addc_u32 s7, s25, s7
	v_mad_u64_u32 v[0:1], s[24:25], v1, s9, v[0:1]
	v_or_b32_e32 v0, v0, v12
	v_lshl_add_u64 v[136:137], s[52:53], 0, v[112:113]
	v_add_lshl_u32 v112, v0, v13, 1
	v_lshrrev_b32_e32 v1, 1, v14
	v_mul_lo_u32 v0, v16, s56
	v_mad_u64_u32 v[0:1], s[24:25], v1, s9, v[0:1]
	s_waitcnt vmcnt(6)
	v_or_b32_e32 v0, v0, v15
	v_lshl_add_u64 v[138:139], s[6:7], 0, v[112:113]
	v_add_lshl_u32 v112, v0, v17, 1
	v_mov_b32_e32 v0, 0
	v_lshl_add_u64 v[140:141], s[6:7], 0, v[112:113]
	s_mov_b32 s6, 0
	v_add_u32_e32 v112, 0, v26
	v_mov_b32_e32 v1, v0
	v_mov_b32_e32 v2, v0
	v_mov_b32_e32 v3, v0
	v_mov_b32_e32 v4, v0
	v_mov_b32_e32 v5, v0
	v_mov_b32_e32 v6, v0
	v_mov_b32_e32 v7, v0
	v_mov_b32_e32 v8, v0
	v_mov_b32_e32 v9, v0
	v_mov_b32_e32 v10, v0
	v_mov_b32_e32 v11, v0
	v_mov_b32_e32 v12, v0
	v_mov_b32_e32 v13, v0
	v_mov_b32_e32 v14, v0
	v_mov_b32_e32 v15, v0
	v_mov_b32_e32 v16, v0
	v_mov_b32_e32 v17, v0
	v_mov_b32_e32 v18, v0
	v_mov_b32_e32 v19, v0
	v_mov_b32_e32 v20, v0
	v_mov_b32_e32 v21, v0
	v_mov_b32_e32 v22, v0
	v_mov_b32_e32 v23, v0
	v_mov_b32_e32 v24, v0
	v_mov_b32_e32 v25, v0
	v_mov_b32_e32 v26, v0
	v_mov_b32_e32 v27, v0
	v_mov_b32_e32 v28, v0
	v_mov_b32_e32 v29, v0
	v_mov_b32_e32 v30, v0
	v_mov_b32_e32 v31, v0
	v_mov_b32_e32 v32, v0
	v_mov_b32_e32 v33, v0
	v_mov_b32_e32 v34, v0
	v_mov_b32_e32 v35, v0
	v_mov_b32_e32 v36, v0
	v_mov_b32_e32 v37, v0
	v_mov_b32_e32 v38, v0
	v_mov_b32_e32 v39, v0
	v_mov_b32_e32 v40, v0
	v_mov_b32_e32 v41, v0
	v_mov_b32_e32 v42, v0
	v_mov_b32_e32 v43, v0
	v_mov_b32_e32 v44, v0
	v_mov_b32_e32 v45, v0
	v_mov_b32_e32 v46, v0
	v_mov_b32_e32 v47, v0
	v_mov_b32_e32 v48, v0
	v_mov_b32_e32 v49, v0
	v_mov_b32_e32 v50, v0
	v_mov_b32_e32 v51, v0
	v_mov_b32_e32 v52, v0
	v_mov_b32_e32 v53, v0
	v_mov_b32_e32 v54, v0
	v_mov_b32_e32 v55, v0
	v_mov_b32_e32 v56, v0
	v_mov_b32_e32 v57, v0
	v_mov_b32_e32 v58, v0
	v_mov_b32_e32 v59, v0
	v_mov_b32_e32 v60, v0
	v_mov_b32_e32 v61, v0
	v_mov_b32_e32 v62, v0
	v_mov_b32_e32 v63, v0
	v_mov_b32_e32 v68, v0
	v_mov_b32_e32 v69, v0
	v_mov_b32_e32 v70, v0
	v_mov_b32_e32 v71, v0
	v_mov_b32_e32 v80, v0
	v_mov_b32_e32 v81, v0
	v_mov_b32_e32 v82, v0
	v_mov_b32_e32 v83, v0
	v_mov_b32_e32 v84, v0
	v_mov_b32_e32 v85, v0
	v_mov_b32_e32 v86, v0
	v_mov_b32_e32 v87, v0
	v_mov_b32_e32 v88, v0
	v_mov_b32_e32 v89, v0
	v_mov_b32_e32 v90, v0
	v_mov_b32_e32 v91, v0
	v_mov_b32_e32 v92, v0
	v_mov_b32_e32 v93, v0
	v_mov_b32_e32 v94, v0
	v_mov_b32_e32 v95, v0
	v_mov_b32_e32 v96, v0
	v_mov_b32_e32 v97, v0
	v_mov_b32_e32 v98, v0
	v_mov_b32_e32 v99, v0
	v_mov_b32_e32 v100, v0
	v_mov_b32_e32 v101, v0
	v_mov_b32_e32 v102, v0
	v_mov_b32_e32 v103, v0
	v_mov_b32_e32 v104, v0
	v_mov_b32_e32 v105, v0
	v_mov_b32_e32 v106, v0
	v_mov_b32_e32 v107, v0
	v_mov_b32_e32 v108, v0
	v_mov_b32_e32 v109, v0
	v_mov_b32_e32 v110, v0
	v_mov_b32_e32 v111, v0
	v_mov_b32_e32 v114, v0
	v_mov_b32_e32 v115, v0
	v_mov_b32_e32 v116, v0
	v_mov_b32_e32 v117, v0
	v_mov_b32_e32 v118, v0
	v_mov_b32_e32 v119, v0
	v_mov_b32_e32 v120, v0
	v_mov_b32_e32 v121, v0
	v_mov_b32_e32 v122, v0
	v_mov_b32_e32 v123, v0
	v_mov_b32_e32 v124, v0
	v_mov_b32_e32 v125, v0
	v_mov_b32_e32 v126, v0
	v_mov_b32_e32 v127, v0
	v_mov_b32_e32 v128, v0
	v_mov_b32_e32 v129, v0
	v_mov_b32_e32 v64, v0
	v_mov_b32_e32 v65, v0
	v_mov_b32_e32 v66, v0
	v_mov_b32_e32 v67, v0
	v_mov_b32_e32 v72, v0
	v_mov_b32_e32 v73, v0
	v_mov_b32_e32 v74, v0
	v_mov_b32_e32 v75, v0
	v_mov_b32_e32 v76, v0
	v_mov_b32_e32 v77, v0
	v_mov_b32_e32 v78, v0
	v_mov_b32_e32 v79, v0
	s_barrier
